# combined: x1rows second-half loads hoisted and row loads ahead of the ssq wait, states tile staging unrolled, scan 8 chunks per iteration, ssdc dt loads at item start
# baseline (speedup 1.0000x reference)
; #define LAS __attribute__((address_space(3)))
; __device__ __forceinline__ int ltid() { int t = threadIdx.x; asm volatile("" : "+v"(t)); return t; }
; __device__ __forceinline__ void ld_tile(LAS unsigned char* dst, const bf16_t* src, int rows) {
;     for (int p = ltid(); p < rows * 16; p += 512) { const int r = p >> 4, c = p & 15; *(LAS u32x4*)(dst + r * SP + c * 16) = *(const u32x4*)(src + r * 128 + c * 8); }
; }
.LBB0_795:
	v_mov_b32_e32 v186, v4
	v_ashrrev_i32_e32 v187, 4, v186
	v_lshlrev_b32_e32 v184, 7, v187
	v_ashrrev_i32_e32 v185, 31, v184
	v_lshl_add_u64 v[184:185], v[184:185], 1, v[2:3]
	global_load_dwordx4 v[144:147], v[184:185], off
	v_mad_u32_u24 v176, v187, s29, v0
	v_add_u32_e32 v186, 0x200, v4
	v_ashrrev_i32_e32 v187, 4, v186
	v_lshlrev_b32_e32 v184, 7, v187
	v_ashrrev_i32_e32 v185, 31, v184
	v_lshl_add_u64 v[184:185], v[184:185], 1, v[2:3]
	global_load_dwordx4 v[148:151], v[184:185], off
	v_mad_u32_u24 v177, v187, s29, v0
	v_add_u32_e32 v186, 0x400, v4
	v_ashrrev_i32_e32 v187, 4, v186
	v_lshlrev_b32_e32 v184, 7, v187
	v_ashrrev_i32_e32 v185, 31, v184
	v_lshl_add_u64 v[184:185], v[184:185], 1, v[2:3]
	global_load_dwordx4 v[152:155], v[184:185], off
	v_mad_u32_u24 v178, v187, s29, v0
	v_add_u32_e32 v186, 0x600, v4
	v_ashrrev_i32_e32 v187, 4, v186
	v_lshlrev_b32_e32 v184, 7, v187
	v_ashrrev_i32_e32 v185, 31, v184
	v_lshl_add_u64 v[184:185], v[184:185], 1, v[2:3]
	global_load_dwordx4 v[156:159], v[184:185], off
	v_mad_u32_u24 v179, v187, s29, v0
	v_add_u32_e32 v186, 0x800, v4
	v_ashrrev_i32_e32 v187, 4, v186
	v_lshlrev_b32_e32 v184, 7, v187
	v_ashrrev_i32_e32 v185, 31, v184
	v_lshl_add_u64 v[184:185], v[184:185], 1, v[2:3]
	global_load_dwordx4 v[160:163], v[184:185], off
	v_mad_u32_u24 v180, v187, s29, v0
	v_add_u32_e32 v186, 0xa00, v4
	v_ashrrev_i32_e32 v187, 4, v186
	v_lshlrev_b32_e32 v184, 7, v187
	v_ashrrev_i32_e32 v185, 31, v184
	v_lshl_add_u64 v[184:185], v[184:185], 1, v[2:3]
	global_load_dwordx4 v[164:167], v[184:185], off
	v_mad_u32_u24 v181, v187, s29, v0
	v_add_u32_e32 v186, 0xc00, v4
	v_ashrrev_i32_e32 v187, 4, v186
	v_lshlrev_b32_e32 v184, 7, v187
	v_ashrrev_i32_e32 v185, 31, v184
	v_lshl_add_u64 v[184:185], v[184:185], 1, v[2:3]
	global_load_dwordx4 v[168:171], v[184:185], off
	v_mad_u32_u24 v182, v187, s29, v0
	v_add_u32_e32 v186, 0xe00, v4
	v_ashrrev_i32_e32 v187, 4, v186
	v_lshlrev_b32_e32 v184, 7, v187
	v_ashrrev_i32_e32 v185, 31, v184
	v_lshl_add_u64 v[184:185], v[184:185], 1, v[2:3]
	global_load_dwordx4 v[172:175], v[184:185], off
	v_mad_u32_u24 v183, v187, s29, v0
	s_waitcnt vmcnt(7)
	ds_write_b128 v176, v[144:147]
	s_waitcnt vmcnt(6)
	ds_write_b128 v177, v[148:151]
	s_waitcnt vmcnt(5)
	ds_write_b128 v178, v[152:155]
	s_waitcnt vmcnt(4)
	ds_write_b128 v179, v[156:159]
	s_waitcnt vmcnt(3)
	ds_write_b128 v180, v[160:163]
	s_waitcnt vmcnt(2)
	ds_write_b128 v181, v[164:167]
	s_waitcnt vmcnt(1)
	ds_write_b128 v182, v[168:171]
	s_waitcnt vmcnt(0)
	ds_write_b128 v183, v[172:175]

; #define LAS __attribute__((address_space(3)))
; __device__ __forceinline__ int ltid() { int t = threadIdx.x; asm volatile("" : "+v"(t)); return t; }
; __device__ __forceinline__ void ld_tile(LAS unsigned char* dst, const bf16_t* src, int rows) {
;     for (int p = ltid(); p < rows * 16; p += 512) { const int r = p >> 4, c = p & 15; *(LAS u32x4*)(dst + r * SP + c * 16) = *(const u32x4*)(src + r * 128 + c * 8); }
; }
.LBB0_798:
	v_mov_b32_e32 v186, v4
	v_ashrrev_i32_e32 v187, 4, v186
	v_lshlrev_b32_e32 v184, 7, v187
	v_ashrrev_i32_e32 v185, 31, v184
	v_lshl_add_u64 v[184:185], v[184:185], 1, v[2:3]
	global_load_dwordx4 v[144:147], v[184:185], off
	v_mad_u32_u24 v176, v187, s29, v0
	v_add_u32_e32 v186, 0x200, v4
	v_ashrrev_i32_e32 v187, 4, v186
	v_lshlrev_b32_e32 v184, 7, v187
	v_ashrrev_i32_e32 v185, 31, v184
	v_lshl_add_u64 v[184:185], v[184:185], 1, v[2:3]
	global_load_dwordx4 v[148:151], v[184:185], off
	v_mad_u32_u24 v177, v187, s29, v0
	v_add_u32_e32 v186, 0x400, v4
	v_ashrrev_i32_e32 v187, 4, v186
	v_lshlrev_b32_e32 v184, 7, v187
	v_ashrrev_i32_e32 v185, 31, v184
	v_lshl_add_u64 v[184:185], v[184:185], 1, v[2:3]
	global_load_dwordx4 v[152:155], v[184:185], off
	v_mad_u32_u24 v178, v187, s29, v0
	v_add_u32_e32 v186, 0x600, v4
	v_ashrrev_i32_e32 v187, 4, v186
	v_lshlrev_b32_e32 v184, 7, v187
	v_ashrrev_i32_e32 v185, 31, v184
	v_lshl_add_u64 v[184:185], v[184:185], 1, v[2:3]
	global_load_dwordx4 v[156:159], v[184:185], off
	v_mad_u32_u24 v179, v187, s29, v0
	s_waitcnt vmcnt(3)
	ds_write_b128 v176, v[144:147]
	s_waitcnt vmcnt(2)
	ds_write_b128 v177, v[148:151]
	s_waitcnt vmcnt(1)
	ds_write_b128 v178, v[152:155]
	s_waitcnt vmcnt(0)
	ds_write_b128 v179, v[156:159]

; __device__ __forceinline__ void st8(bf16_t* p, f32x4 a, f32x4 b) { u32x4 w; w.x = pk2(a[0], a[1]); w.y = pk2(a[2], a[3]); w.z = pk2(b[0], b[1]); w.w = pk2(b[2], b[3]); *(u32x4*)p = w; }
; __device__ __forceinline__ void ld8(const bf16_t* p, f32x4& a, f32x4& b) { const u32x4 w = *(const u32x4*)p; a[0] = bflo(w.x); a[1] = bfhi(w.x); a[2] = bflo(w.y); a[3] = bfhi(w.y); b[0] = bflo(w.z); b[1] = bfhi(w.z); b[2] = bflo(w.w); b[3] = bfhi(w.w); }
; __device__ __forceinline__ void ph_scan() {
;     ...
; #pragma unroll 4
;         for (int c = 0; c < 32; ++c) { const unsigned off = (unsigned)(((b * 32 + c) * 32 + gh) * 8192 + pn8 * 8);
;             f32x4 a0, a1; ld8(ST + off, a0, a1); st8(HP + off, s0, s1);
;             const float d = DEC[(b * 32 + c) * 32 + gh]; s0 = s0 * d + a0; s1 = s1 * d + a1; }
.LBB0_863:
	v_add_u32_e32 v0, 0xfff40000, v2
	v_lshlrev_b64 v[72:73], 1, v[0:1]
	v_add_u32_e32 v0, 0xfff80000, v2
	v_lshlrev_b64 v[74:75], 1, v[0:1]
	v_add_u32_e32 v0, 0xfffc0000, v2
	v_lshlrev_b64 v[76:77], 1, v[0:1]
	v_mov_b32_e32 v3, v1
	v_lshlrev_b64 v[78:79], 1, v[2:3]
	v_add_u32_e32 v0, 0x40000, v2
	v_lshlrev_b64 v[154:155], 1, v[0:1]
	v_add_u32_e32 v0, 0x80000, v2
	v_lshlrev_b64 v[156:157], 1, v[0:1]
	v_add_u32_e32 v0, 0xc0000, v2
	v_lshlrev_b64 v[158:159], 1, v[0:1]
	v_add_u32_e32 v0, 0x100000, v2
	v_lshlrev_b64 v[160:161], 1, v[0:1]
	v_lshl_add_u64 v[68:69], s[6:7], 0, v[72:73]
	global_load_dwordx4 v[40:43], v[68:69], off
	v_lshl_add_u64 v[68:69], s[6:7], 0, v[74:75]
	global_load_dwordx4 v[44:47], v[68:69], off
	v_lshl_add_u64 v[68:69], s[6:7], 0, v[76:77]
	global_load_dwordx4 v[48:51], v[68:69], off
	v_lshl_add_u64 v[68:69], s[6:7], 0, v[78:79]
	global_load_dwordx4 v[56:59], v[68:69], off
	v_lshl_add_u64 v[68:69], s[6:7], 0, v[154:155]
	global_load_dwordx4 v[112:115], v[68:69], off
	v_lshl_add_u64 v[68:69], s[6:7], 0, v[156:157]
	global_load_dwordx4 v[116:119], v[68:69], off
	v_lshl_add_u64 v[68:69], s[6:7], 0, v[158:159]
	global_load_dwordx4 v[120:123], v[68:69], off
	v_lshl_add_u64 v[68:69], s[6:7], 0, v[160:161]
	global_load_dwordx4 v[144:147], v[68:69], off
	v_add_u32_e32 v4, s10, v16
	v_ashrrev_i32_e32 v5, 31, v4
	v_lshl_add_u64 v[68:69], v[4:5], 2, s[40:41]
	global_load_dword v60, v[68:69], off
	v_add_u32_e32 v70, 32, v4
	v_ashrrev_i32_e32 v71, 31, v70
	v_lshl_add_u64 v[68:69], v[70:71], 2, s[40:41]
	global_load_dword v62, v[68:69], off
	v_add_u32_e32 v70, 64, v4
	v_ashrrev_i32_e32 v71, 31, v70
	v_lshl_add_u64 v[68:69], v[70:71], 2, s[40:41]
	global_load_dword v64, v[68:69], off
	v_add_u32_e32 v70, 0x60, v4
	v_ashrrev_i32_e32 v71, 31, v70
	v_lshl_add_u64 v[68:69], v[70:71], 2, s[40:41]
	global_load_dword v66, v[68:69], off
	v_add_u32_e32 v70, 0x80, v4
	v_ashrrev_i32_e32 v71, 31, v70
	v_lshl_add_u64 v[68:69], v[70:71], 2, s[40:41]
	global_load_dword v124, v[68:69], off
	v_add_u32_e32 v70, 0xa0, v4
	v_ashrrev_i32_e32 v71, 31, v70
	v_lshl_add_u64 v[68:69], v[70:71], 2, s[40:41]
	global_load_dword v148, v[68:69], off
	v_add_u32_e32 v70, 0xc0, v4
	v_ashrrev_i32_e32 v71, 31, v70
	v_lshl_add_u64 v[68:69], v[70:71], 2, s[40:41]
	global_load_dword v150, v[68:69], off
	v_add_u32_e32 v70, 0xe0, v4
	v_ashrrev_i32_e32 v71, 31, v70
	v_lshl_add_u64 v[68:69], v[70:71], 2, s[40:41]
	global_load_dword v152, v[68:69], off
	v_add_u32_e32 v2, 0x200000, v2
	s_addk_i32 s10, 0x100
	s_cmpk_eq_i32 s10, 0x400
	v_lshl_add_u64 v[72:73], s[38:39], 0, v[72:73]
	v_lshl_add_u64 v[74:75], s[38:39], 0, v[74:75]
	v_lshl_add_u64 v[76:77], s[38:39], 0, v[76:77]
	v_lshl_add_u64 v[78:79], s[38:39], 0, v[78:79]
	v_lshl_add_u64 v[154:155], s[38:39], 0, v[154:155]
	v_lshl_add_u64 v[156:157], s[38:39], 0, v[156:157]
	v_lshl_add_u64 v[158:159], s[38:39], 0, v[158:159]
	v_lshl_add_u64 v[160:161], s[38:39], 0, v[160:161]
	s_waitcnt vmcnt(0)
; __device__ __forceinline__ void st8(bf16_t* p, f32x4 a, f32x4 b) { u32x4 w; w.x = pk2(a[0], a[1]); w.y = pk2(a[2], a[3]); w.z = pk2(b[0], b[1]); w.w = pk2(b[2], b[3]); *(u32x4*)p = w; }
; __device__ __forceinline__ void ld8(const bf16_t* p, f32x4& a, f32x4& b) { const u32x4 w = *(const u32x4*)p; a[0] = bflo(w.x); a[1] = bfhi(w.x); a[2] = bflo(w.y); a[3] = bfhi(w.y); b[0] = bflo(w.z); b[1] = bfhi(w.z); b[2] = bflo(w.w); b[3] = bfhi(w.w); }
; __device__ __forceinline__ void ph_scan() {
;     ...
;         for (int c = 0; c < 32; ++c) { const unsigned off = (unsigned)(((b * 32 + c) * 32 + gh) * 8192 + pn8 * 8);
;             f32x4 a0, a1; ld8(ST + off, a0, a1); st8(HP + off, s0, s1);
;             const float d = DEC[(b * 32 + c) * 32 + gh]; s0 = s0 * d + a0; s1 = s1 * d + a1; }
	v_cvt_pk_bf16_f32 v18, v10, v11
	v_cvt_pk_bf16_f32 v19, v12, v13
	v_cvt_pk_bf16_f32 v20, v6, v7
	v_cvt_pk_bf16_f32 v21, v8, v9
	global_store_dwordx4 v[72:73], v[18:21], off
	v_lshlrev_b32_e32 v24, 16, v40
	v_and_b32_e32 v25, 0xffff0000, v40
	v_lshlrev_b32_e32 v26, 16, v41
	v_and_b32_e32 v27, 0xffff0000, v41
	v_lshlrev_b32_e32 v28, 16, v42
	v_and_b32_e32 v29, 0xffff0000, v42
	v_lshlrev_b32_e32 v30, 16, v43
	v_and_b32_e32 v31, 0xffff0000, v43
	v_pk_fma_f32 v[10:11], v[10:11], v[60:61], v[24:25] op_sel_hi:[1,0,1]
	v_pk_fma_f32 v[12:13], v[12:13], v[60:61], v[26:27] op_sel_hi:[1,0,1]
	v_pk_fma_f32 v[6:7], v[6:7], v[60:61], v[28:29] op_sel_hi:[1,0,1]
	v_pk_fma_f32 v[8:9], v[8:9], v[60:61], v[30:31] op_sel_hi:[1,0,1]
	v_cvt_pk_bf16_f32 v18, v10, v11
	v_cvt_pk_bf16_f32 v19, v12, v13
	v_cvt_pk_bf16_f32 v20, v6, v7
	v_cvt_pk_bf16_f32 v21, v8, v9
	global_store_dwordx4 v[74:75], v[18:21], off
	v_lshlrev_b32_e32 v24, 16, v44
	v_and_b32_e32 v25, 0xffff0000, v44
	v_lshlrev_b32_e32 v26, 16, v45
	v_and_b32_e32 v27, 0xffff0000, v45
	v_lshlrev_b32_e32 v28, 16, v46
	v_and_b32_e32 v29, 0xffff0000, v46
	v_lshlrev_b32_e32 v30, 16, v47
	v_and_b32_e32 v31, 0xffff0000, v47
	v_pk_fma_f32 v[10:11], v[10:11], v[62:63], v[24:25] op_sel_hi:[1,0,1]
	v_pk_fma_f32 v[12:13], v[12:13], v[62:63], v[26:27] op_sel_hi:[1,0,1]
	v_pk_fma_f32 v[6:7], v[6:7], v[62:63], v[28:29] op_sel_hi:[1,0,1]
	v_pk_fma_f32 v[8:9], v[8:9], v[62:63], v[30:31] op_sel_hi:[1,0,1]
	v_cvt_pk_bf16_f32 v18, v10, v11
	v_cvt_pk_bf16_f32 v19, v12, v13
	v_cvt_pk_bf16_f32 v20, v6, v7
	v_cvt_pk_bf16_f32 v21, v8, v9
	global_store_dwordx4 v[76:77], v[18:21], off
	v_lshlrev_b32_e32 v24, 16, v48
	v_and_b32_e32 v25, 0xffff0000, v48
	v_lshlrev_b32_e32 v26, 16, v49
	v_and_b32_e32 v27, 0xffff0000, v49
	v_lshlrev_b32_e32 v28, 16, v50
	v_and_b32_e32 v29, 0xffff0000, v50
	v_lshlrev_b32_e32 v30, 16, v51
	v_and_b32_e32 v31, 0xffff0000, v51
	v_pk_fma_f32 v[10:11], v[10:11], v[64:65], v[24:25] op_sel_hi:[1,0,1]
	v_pk_fma_f32 v[12:13], v[12:13], v[64:65], v[26:27] op_sel_hi:[1,0,1]
	v_pk_fma_f32 v[6:7], v[6:7], v[64:65], v[28:29] op_sel_hi:[1,0,1]
	v_pk_fma_f32 v[8:9], v[8:9], v[64:65], v[30:31] op_sel_hi:[1,0,1]
	v_cvt_pk_bf16_f32 v18, v10, v11
	v_cvt_pk_bf16_f32 v19, v12, v13
	v_cvt_pk_bf16_f32 v20, v6, v7
	v_cvt_pk_bf16_f32 v21, v8, v9
	global_store_dwordx4 v[78:79], v[18:21], off
	v_lshlrev_b32_e32 v24, 16, v56
	v_and_b32_e32 v25, 0xffff0000, v56
	v_lshlrev_b32_e32 v26, 16, v57
	v_and_b32_e32 v27, 0xffff0000, v57
	v_lshlrev_b32_e32 v28, 16, v58
	v_and_b32_e32 v29, 0xffff0000, v58
	v_lshlrev_b32_e32 v30, 16, v59
	v_and_b32_e32 v31, 0xffff0000, v59
	v_pk_fma_f32 v[10:11], v[10:11], v[66:67], v[24:25] op_sel_hi:[1,0,1]
	v_pk_fma_f32 v[12:13], v[12:13], v[66:67], v[26:27] op_sel_hi:[1,0,1]
	v_pk_fma_f32 v[6:7], v[6:7], v[66:67], v[28:29] op_sel_hi:[1,0,1]
	v_pk_fma_f32 v[8:9], v[8:9], v[66:67], v[30:31] op_sel_hi:[1,0,1]
	v_cvt_pk_bf16_f32 v18, v10, v11
	v_cvt_pk_bf16_f32 v19, v12, v13
	v_cvt_pk_bf16_f32 v20, v6, v7
	v_cvt_pk_bf16_f32 v21, v8, v9
	global_store_dwordx4 v[154:155], v[18:21], off
	v_lshlrev_b32_e32 v24, 16, v112
	v_and_b32_e32 v25, 0xffff0000, v112
	v_lshlrev_b32_e32 v26, 16, v113
	v_and_b32_e32 v27, 0xffff0000, v113
	v_lshlrev_b32_e32 v28, 16, v114
	v_and_b32_e32 v29, 0xffff0000, v114
	v_lshlrev_b32_e32 v30, 16, v115
	v_and_b32_e32 v31, 0xffff0000, v115
	v_pk_fma_f32 v[10:11], v[10:11], v[124:125], v[24:25] op_sel_hi:[1,0,1]
	v_pk_fma_f32 v[12:13], v[12:13], v[124:125], v[26:27] op_sel_hi:[1,0,1]
	v_pk_fma_f32 v[6:7], v[6:7], v[124:125], v[28:29] op_sel_hi:[1,0,1]
	v_pk_fma_f32 v[8:9], v[8:9], v[124:125], v[30:31] op_sel_hi:[1,0,1]
	v_cvt_pk_bf16_f32 v18, v10, v11
	v_cvt_pk_bf16_f32 v19, v12, v13
	v_cvt_pk_bf16_f32 v20, v6, v7
	v_cvt_pk_bf16_f32 v21, v8, v9
	global_store_dwordx4 v[156:157], v[18:21], off
	v_lshlrev_b32_e32 v24, 16, v116
	v_and_b32_e32 v25, 0xffff0000, v116
	v_lshlrev_b32_e32 v26, 16, v117
	v_and_b32_e32 v27, 0xffff0000, v117
	v_lshlrev_b32_e32 v28, 16, v118
	v_and_b32_e32 v29, 0xffff0000, v118
	v_lshlrev_b32_e32 v30, 16, v119
	v_and_b32_e32 v31, 0xffff0000, v119
	v_pk_fma_f32 v[10:11], v[10:11], v[148:149], v[24:25] op_sel_hi:[1,0,1]
	v_pk_fma_f32 v[12:13], v[12:13], v[148:149], v[26:27] op_sel_hi:[1,0,1]
	v_pk_fma_f32 v[6:7], v[6:7], v[148:149], v[28:29] op_sel_hi:[1,0,1]
	v_pk_fma_f32 v[8:9], v[8:9], v[148:149], v[30:31] op_sel_hi:[1,0,1]
	v_cvt_pk_bf16_f32 v18, v10, v11
	v_cvt_pk_bf16_f32 v19, v12, v13
	v_cvt_pk_bf16_f32 v20, v6, v7
	v_cvt_pk_bf16_f32 v21, v8, v9
	global_store_dwordx4 v[158:159], v[18:21], off
	v_lshlrev_b32_e32 v24, 16, v120
	v_and_b32_e32 v25, 0xffff0000, v120
	v_lshlrev_b32_e32 v26, 16, v121
	v_and_b32_e32 v27, 0xffff0000, v121
	v_lshlrev_b32_e32 v28, 16, v122
	v_and_b32_e32 v29, 0xffff0000, v122
	v_lshlrev_b32_e32 v30, 16, v123
	v_and_b32_e32 v31, 0xffff0000, v123
	v_pk_fma_f32 v[10:11], v[10:11], v[150:151], v[24:25] op_sel_hi:[1,0,1]
	v_pk_fma_f32 v[12:13], v[12:13], v[150:151], v[26:27] op_sel_hi:[1,0,1]
	v_pk_fma_f32 v[6:7], v[6:7], v[150:151], v[28:29] op_sel_hi:[1,0,1]
	v_pk_fma_f32 v[8:9], v[8:9], v[150:151], v[30:31] op_sel_hi:[1,0,1]
	v_cvt_pk_bf16_f32 v18, v10, v11
	v_cvt_pk_bf16_f32 v19, v12, v13
	v_cvt_pk_bf16_f32 v20, v6, v7
	v_cvt_pk_bf16_f32 v21, v8, v9
	global_store_dwordx4 v[160:161], v[18:21], off
	v_lshlrev_b32_e32 v24, 16, v144
	v_and_b32_e32 v25, 0xffff0000, v144
	v_lshlrev_b32_e32 v26, 16, v145
	v_and_b32_e32 v27, 0xffff0000, v145
	v_lshlrev_b32_e32 v28, 16, v146
	v_and_b32_e32 v29, 0xffff0000, v146
	v_lshlrev_b32_e32 v30, 16, v147
	v_and_b32_e32 v31, 0xffff0000, v147
	v_pk_fma_f32 v[10:11], v[10:11], v[152:153], v[24:25] op_sel_hi:[1,0,1]
	v_pk_fma_f32 v[12:13], v[12:13], v[152:153], v[26:27] op_sel_hi:[1,0,1]
	v_pk_fma_f32 v[6:7], v[6:7], v[152:153], v[28:29] op_sel_hi:[1,0,1]
	v_pk_fma_f32 v[8:9], v[8:9], v[152:153], v[30:31] op_sel_hi:[1,0,1]
	s_cbranch_scc0 .LBB0_863
	v_add_u32_e32 v14, s8, v14
	s_mov_b32 s2, 0x1ffff
	v_cmp_lt_i32_e32 vcc, s2, v14
	s_or_b64 s[42:43], vcc, s[42:43]
	v_add_u32_e32 v15, s9, v15
	s_andn2_b64 exec, exec, s[42:43]
	s_cbranch_execnz .LBB0_862

; __device__ __forceinline__ float dot4(f32x4 a) { return (a[0] * a[0] + a[1] * a[1]) + (a[2] * a[2] + a[3] * a[3]); }
; __device__ __forceinline__ void ph_x1rows(int tbase) {
;     ...
;     for (int m = gw; m < TG; m += NGW) { const int t = tbase + m, b = t >> 12;
;         float sv = lane < 16 ? SSQ_MIX[lane * TT + t] : 0.f; sv += __shfl_xor(sv, 1); sv += __shfl_xor(sv, 2); sv += __shfl_xor(sv, 4); sv += __shfl_xor(sv, 8); sv = __shfl(sv, 0);
;         const float rs1 = rsqrtf(sv * (1.f / 1024.f) + EPS); const float* mod = MOD + b * 6144;
;         f32x4 v[4]; float s = 0.f;
; #pragma unroll
;         for (int j = 0; j < 4; ++j) { const int c0 = 4 * lane + 256 * j; const u32x2 w = *(const u32x2*)(MIX + (size_t)m * 1024 + c0);
;             const f32x4 f = {bflo(w.x), bfhi(w.x), bflo(w.y), bfhi(w.y)}; const f32x4 g = *(const f32x4*)(g_post_mix + c0), ga = *(const f32x4*)(mod + 2048 + c0);
;             v[j] = *(const f32x4*)(x + (size_t)t * 1024 + c0) + ga * (f * rs1 * g); *(f32x4*)(out + (size_t)t * 1024 + c0) = v[j]; s += dot4(v[j]); }
.LBB0_1217:
	s_or_b64 exec, exec, s[8:9]
	s_add_i32 s10, s63, s4
	s_ashr_i32 s2, s10, 12
	s_mul_i32 s8, s2, 0x1800
	s_ashr_i32 s9, s8, 31
	s_lshl_b64 s[8:9], s[8:9], 2
	s_add_u32 s5, s12, s8
	s_addc_u32 s7, s13, s9
	s_add_u32 s8, s5, 0x2000
	s_addc_u32 s9, s7, 0
	s_ashr_i32 s11, s10, 31
	s_lshl_b64 s[10:11], s[10:11], 12
	v_lshl_add_u64 v[6:7], v[22:23], 0, s[10:11]
	s_add_u32 s64, s5, 0x4000
	s_addc_u32 s65, s7, 0
	s_add_u32 s72, s5, 0x3000
	s_addc_u32 s73, s7, 0
	global_load_dwordx2 v[144:145], v[26:27], off
	global_load_dwordx2 v[146:147], v[26:27], off offset:512
	global_load_dwordx2 v[148:149], v[26:27], off offset:1024
	global_load_dwordx2 v[150:151], v[26:27], off offset:1536
	global_load_dwordx4 v[152:155], v[20:21], off
	global_load_dwordx4 v[168:171], v37, s[8:9]
	global_load_dwordx4 v[184:187], v[6:7], off
	global_load_dwordx4 v[156:159], v[20:21], off offset:1024
	global_load_dwordx4 v[172:175], v38, s[8:9]
	global_load_dwordx4 v[188:191], v[6:7], off offset:1024
	global_load_dwordx4 v[160:163], v[20:21], off offset:2048
	global_load_dwordx4 v[176:179], v39, s[8:9]
	global_load_dwordx4 v[192:195], v[6:7], off offset:2048
	global_load_dwordx4 v[164:167], v[20:21], off offset:3072
	global_load_dwordx4 v[180:183], v40, s[8:9]
	global_load_dwordx4 v[196:199], v[6:7], off offset:3072
	s_mov_b32 s2, 0xe7c00000
	s_add_i32 s4, s4, s6
	s_cmpk_lt_i32 s4, 0x4000
	s_waitcnt vmcnt(16)
	ds_bpermute_b32 v2, v30, v0
	s_waitcnt lgkmcnt(0)
	v_add_f32_e32 v0, v0, v2
	ds_bpermute_b32 v2, v31, v0
	s_waitcnt lgkmcnt(0)
	v_add_f32_e32 v0, v0, v2
	ds_bpermute_b32 v2, v32, v0
	s_waitcnt lgkmcnt(0)
	v_add_f32_e32 v0, v0, v2
	ds_bpermute_b32 v2, v33, v0
	s_waitcnt lgkmcnt(0)
	v_add_f32_e32 v0, v0, v2
	ds_bpermute_b32 v0, v244, v0
	s_waitcnt lgkmcnt(0)
	v_fmamk_f32 v0, v0, 0x3a800000, v220
	v_cmp_gt_f32_e64 s[38:39], s51, v0
	v_mul_f32_e32 v2, 0x4b800000, v0
	s_nop 0
	v_cndmask_b32_e64 v0, v0, v2, s[38:39]
	v_rsq_f32_e32 v0, v0
	s_nop 0
	v_mul_f32_e32 v2, 0x45800000, v0
	v_cndmask_b32_e64 v0, v0, v2, s[38:39]
	s_waitcnt vmcnt(12)
	v_lshlrev_b32_e32 v16, 16, v144
	v_and_b32_e32 v17, 0xffff0000, v144
	v_lshlrev_b32_e32 v28, 16, v145
	v_and_b32_e32 v29, 0xffff0000, v145
	v_pk_mul_f32 v[28:29], v[0:1], v[28:29] op_sel_hi:[0,1]
	v_pk_mul_f32 v[16:17], v[0:1], v[16:17] op_sel_hi:[0,1]
	s_waitcnt vmcnt(11)
	v_pk_mul_f32 v[2:3], v[152:153], v[16:17]
	v_pk_mul_f32 v[4:5], v[154:155], v[28:29]
	v_lshl_add_u64 v[28:29], v[24:25], 0, s[10:11]
	s_waitcnt vmcnt(9)
	v_pk_fma_f32 v[16:17], v[170:171], v[4:5], v[186:187]
	v_pk_fma_f32 v[14:15], v[168:169], v[2:3], v[184:185]
	global_store_dwordx4 v[28:29], v[14:17], off
	v_pk_mul_f32 v[2:3], v[16:17], v[16:17]
	v_pk_mul_f32 v[4:5], v[14:15], v[14:15]
	s_nop 0
	v_pk_mov_b32 v[8:9], v[4:5], v[2:3] op_sel:[1,0]
	v_mov_b32_e32 v5, v3
	v_pk_add_f32 v[50:51], v[8:9], v[4:5]
	v_lshlrev_b32_e32 v12, 16, v146
	v_and_b32_e32 v13, 0xffff0000, v146
	v_lshlrev_b32_e32 v46, 16, v147
	v_and_b32_e32 v47, 0xffff0000, v147
	v_pk_mul_f32 v[46:47], v[0:1], v[46:47] op_sel_hi:[0,1]
	v_pk_mul_f32 v[12:13], v[0:1], v[12:13] op_sel_hi:[0,1]
	s_waitcnt vmcnt(9)
	v_pk_mul_f32 v[2:3], v[156:157], v[12:13]
	v_pk_mul_f32 v[4:5], v[158:159], v[46:47]
	s_waitcnt vmcnt(7)
	v_pk_fma_f32 v[12:13], v[174:175], v[4:5], v[190:191]
	v_pk_fma_f32 v[10:11], v[172:173], v[2:3], v[188:189]
	global_store_dwordx4 v[28:29], v[10:13], off offset:1024
	v_pk_mul_f32 v[2:3], v[12:13], v[12:13]
	v_pk_mul_f32 v[4:5], v[10:11], v[10:11]
	s_nop 0
	v_pk_mov_b32 v[8:9], v[4:5], v[2:3] op_sel:[1,0]
	v_mov_b32_e32 v5, v3
	v_pk_add_f32 v[52:53], v[8:9], v[4:5]
	v_lshlrev_b32_e32 v8, 16, v148
	v_and_b32_e32 v9, 0xffff0000, v148
	v_lshlrev_b32_e32 v54, 16, v149
	v_and_b32_e32 v55, 0xffff0000, v149
	v_pk_mul_f32 v[54:55], v[0:1], v[54:55] op_sel_hi:[0,1]
	v_pk_mul_f32 v[8:9], v[0:1], v[8:9] op_sel_hi:[0,1]
	s_waitcnt vmcnt(7)
	v_pk_mul_f32 v[2:3], v[160:161], v[8:9]
	v_pk_mul_f32 v[4:5], v[162:163], v[54:55]
	s_waitcnt vmcnt(5)
	v_pk_fma_f32 v[2:3], v[176:177], v[2:3], v[192:193]
	v_pk_fma_f32 v[4:5], v[178:179], v[4:5], v[194:195]
	global_store_dwordx4 v[28:29], v[2:5], off offset:2048
	v_lshlrev_b32_e32 v54, 16, v150
	v_and_b32_e32 v55, 0xffff0000, v150
	v_lshlrev_b32_e32 v56, 16, v151
	v_and_b32_e32 v57, 0xffff0000, v151
	s_nop 0
	v_pk_mul_f32 v[56:57], v[0:1], v[56:57] op_sel_hi:[0,1]
	v_pk_mul_f32 v[54:55], v[0:1], v[54:55] op_sel_hi:[0,1]
	s_waitcnt vmcnt(5)
	v_pk_mul_f32 v[42:43], v[164:165], v[54:55]
	v_pk_mul_f32 v[44:45], v[166:167], v[56:57]
	s_waitcnt vmcnt(3)
; __device__ __forceinline__ unsigned pk2(float lo, float hi) { const f32x2 v = {lo, hi}; const bf16x2_t b = __builtin_convertvector(v, bf16x2_t); return __builtin_bit_cast(unsigned, b); }
; __device__ __forceinline__ float dot4(f32x4 a) { return (a[0] * a[0] + a[1] * a[1]) + (a[2] * a[2] + a[3] * a[3]); }
; __device__ __forceinline__ void ph_x1rows(int tbase) {
;     ...
;             v[j] = *(const f32x4*)(x + (size_t)t * 1024 + c0) + ga * (f * rs1 * g); *(f32x4*)(out + (size_t)t * 1024 + c0) = v[j]; s += dot4(v[j]); }
;         const float rs2 = rsqrtf(wave_sum(s) * (1.f / 1024.f) + EPS);
; #pragma unroll
;         for (int j = 0; j < 4; ++j) { const int c0 = 4 * lane + 256 * j; const f32x4 g = *(const f32x4*)(g_pre_mlp + c0), sc = *(const f32x4*)(mod + 4096 + c0), sh = *(const f32x4*)(mod + 3072 + c0);
;             const f32x4 hv = v[j] * rs2 * g * (sc + 1.f) + sh; u32x2 w; w.x = pk2(hv[0], hv[1]); w.y = pk2(hv[2], hv[3]); *(u32x2*)(H + (size_t)m * 1024 + c0) = w; } }
	v_pk_fma_f32 v[6:7], v[180:181], v[42:43], v[196:197]
	v_pk_fma_f32 v[8:9], v[182:183], v[44:45], v[198:199]
	global_store_dwordx4 v[28:29], v[6:9], off offset:3072
	v_mul_f32_e32 v0, v6, v6
	v_mul_f32_e32 v41, v7, v7
	v_pk_add_f32 v[28:29], v[50:51], v[50:51] op_sel:[0,1] op_sel_hi:[1,0]
	v_pk_add_f32 v[42:43], v[52:53], v[52:53] op_sel:[0,1] op_sel_hi:[1,0]
	v_mov_b32_e32 v29, v0
	v_mov_b32_e32 v43, v41
	v_mul_f32_e32 v0, v3, v3
	v_mul_f32_e32 v44, v8, v8
	v_pk_add_f32 v[28:29], v[28:29], v[42:43]
	v_pk_fma_f32 v[42:43], v[2:3], v[2:3], v[0:1] op_sel_hi:[1,1,0]
	v_mul_f32_e32 v0, v5, v5
	v_mul_f32_e32 v46, v9, v9
	v_mov_b32_e32 v43, v44
	v_pk_fma_f32 v[44:45], v[4:5], v[4:5], v[0:1] op_sel_hi:[1,1,0]
	s_nop 0
	v_mov_b32_e32 v45, v46
	v_pk_add_f32 v[42:43], v[42:43], v[44:45]
	s_nop 0
	v_pk_add_f32 v[28:29], v[28:29], v[42:43]
	global_load_dwordx4 v[42:45], v[18:19], off
	global_load_dwordx4 v[46:49], v37, s[64:65]
	global_load_dwordx4 v[50:53], v37, s[72:73]
	global_load_dwordx4 v[112:115], v[18:19], off offset:1024
	global_load_dwordx4 v[68:71], v38, s[64:65]
	global_load_dwordx4 v[200:203], v38, s[72:73]
	global_load_dwordx4 v[116:119], v[18:19], off offset:2048
	global_load_dwordx4 v[72:75], v39, s[64:65]
	global_load_dwordx4 v[204:207], v39, s[72:73]
	global_load_dwordx4 v[120:123], v[18:19], off offset:3072
	global_load_dwordx4 v[76:79], v40, s[64:65]
	global_load_dwordx4 v[208:211], v40, s[72:73]
	v_add_f32_e32 v0, v28, v29
	ds_bpermute_b32 v28, v30, v0
	s_waitcnt lgkmcnt(0)
	v_add_f32_e32 v0, v0, v28
	ds_bpermute_b32 v28, v31, v0
	s_waitcnt lgkmcnt(0)
	v_add_f32_e32 v0, v0, v28
	ds_bpermute_b32 v28, v32, v0
	s_waitcnt lgkmcnt(0)
	v_add_f32_e32 v0, v0, v28
	ds_bpermute_b32 v28, v33, v0
	s_waitcnt lgkmcnt(0)
	v_add_f32_e32 v0, v0, v28
	ds_bpermute_b32 v28, v34, v0
	s_waitcnt lgkmcnt(0)
	v_add_f32_e32 v0, v0, v28
	ds_bpermute_b32 v28, v35, v0
	s_waitcnt lgkmcnt(0)
	v_add_f32_e32 v0, v0, v28
	v_fmamk_f32 v0, v0, 0x3a800000, v220
	v_cmp_gt_f32_e64 s[38:39], s51, v0
	v_mul_f32_e32 v28, 0x4b800000, v0
	s_nop 0
	v_cndmask_b32_e64 v0, v0, v28, s[38:39]
	v_rsq_f32_e32 v0, v0
	s_nop 0
	v_mul_f32_e32 v28, 0x45800000, v0
	v_cndmask_b32_e64 v0, v0, v28, s[38:39]
	v_pk_mul_f32 v[16:17], v[16:17], v[0:1] op_sel_hi:[1,0]
	v_pk_mul_f32 v[14:15], v[14:15], v[0:1] op_sel_hi:[1,0]
	v_pk_mul_f32 v[12:13], v[12:13], v[0:1] op_sel_hi:[1,0]
	v_pk_mul_f32 v[10:11], v[10:11], v[0:1] op_sel_hi:[1,0]
	v_pk_mul_f32 v[4:5], v[4:5], v[0:1] op_sel_hi:[1,0]
	v_pk_mul_f32 v[2:3], v[2:3], v[0:1] op_sel_hi:[1,0]
	v_pk_mul_f32 v[8:9], v[8:9], v[0:1] op_sel_hi:[1,0]
	v_pk_mul_f32 v[6:7], v[6:7], v[0:1] op_sel_hi:[1,0]
	s_waitcnt vmcnt(11)
	v_pk_mul_f32 v[14:15], v[42:43], v[14:15]
	v_pk_mul_f32 v[16:17], v[44:45], v[16:17]
	s_waitcnt vmcnt(10)
	v_pk_add_f32 v[28:29], v[48:49], 1.0 op_sel_hi:[1,0]
	v_pk_add_f32 v[42:43], v[46:47], 1.0 op_sel_hi:[1,0]
	s_waitcnt vmcnt(9)
	v_pk_fma_f32 v[16:17], v[28:29], v[16:17], v[52:53]
	v_pk_fma_f32 v[14:15], v[42:43], v[14:15], v[50:51]
	s_nop 0
	v_cvt_pk_bf16_f32 v14, v14, v15
	v_cvt_pk_bf16_f32 v15, v16, v17
	v_add_co_u32_e64 v16, s[38:39], s2, v26
	s_mov_b32 s2, 0xe7c01000
	s_nop 0
	v_addc_co_u32_e64 v17, s[38:39], -1, v27, s[38:39]
	global_store_dwordx2 v[16:17], v[14:15], off
	s_nop 0
	v_add_co_u32_e64 v28, s[38:39], s2, v26
	s_waitcnt vmcnt(9)
	v_pk_mul_f32 v[10:11], v[112:113], v[10:11]
	v_pk_mul_f32 v[12:13], v[114:115], v[12:13]
	s_waitcnt vmcnt(8)
	v_pk_add_f32 v[14:15], v[70:71], 1.0 op_sel_hi:[1,0]
	v_pk_add_f32 v[16:17], v[68:69], 1.0 op_sel_hi:[1,0]
	s_waitcnt vmcnt(7)
	v_pk_fma_f32 v[12:13], v[14:15], v[12:13], v[202:203]
	v_pk_fma_f32 v[10:11], v[16:17], v[10:11], v[200:201]
	v_addc_co_u32_e64 v29, s[38:39], -1, v27, s[38:39]
	v_cvt_pk_bf16_f32 v10, v10, v11
	v_cvt_pk_bf16_f32 v11, v12, v13
	global_store_dwordx2 v[28:29], v[10:11], off offset:-3584
	s_nop 0
	v_lshl_add_u64 v[26:27], v[26:27], 0, s[42:43]
	s_waitcnt vmcnt(7)
	v_pk_mul_f32 v[2:3], v[116:117], v[2:3]
	v_pk_mul_f32 v[4:5], v[118:119], v[4:5]
	s_waitcnt vmcnt(6)
	v_pk_add_f32 v[10:11], v[74:75], 1.0 op_sel_hi:[1,0]
	v_pk_add_f32 v[12:13], v[72:73], 1.0 op_sel_hi:[1,0]
	s_waitcnt vmcnt(5)
	v_pk_fma_f32 v[4:5], v[10:11], v[4:5], v[206:207]
	v_pk_fma_f32 v[2:3], v[12:13], v[2:3], v[204:205]
	s_nop 0
	v_cvt_pk_bf16_f32 v2, v2, v3
	v_cvt_pk_bf16_f32 v3, v4, v5
	global_store_dwordx2 v[28:29], v[2:3], off offset:-3072
	s_nop 0
	s_waitcnt vmcnt(5)
	v_pk_mul_f32 v[2:3], v[120:121], v[6:7]
	v_pk_mul_f32 v[4:5], v[122:123], v[8:9]
	s_waitcnt vmcnt(4)
	v_pk_add_f32 v[6:7], v[78:79], 1.0 op_sel_hi:[1,0]
	v_pk_add_f32 v[8:9], v[76:77], 1.0 op_sel_hi:[1,0]
	s_waitcnt vmcnt(3)
	v_pk_fma_f32 v[4:5], v[6:7], v[4:5], v[210:211]
	v_pk_fma_f32 v[2:3], v[8:9], v[2:3], v[208:209]
	s_nop 0
	v_cvt_pk_bf16_f32 v2, v2, v3
	v_cvt_pk_bf16_f32 v3, v4, v5
	global_store_dwordx2 v[28:29], v[2:3], off offset:-2560
	s_cbranch_scc0 .LBB0_1220
